# pp_v18 + RC1 S3 block recursion: per step all independent LDS reads (both B operands, subtrahends) issued together at the top
# baseline (speedup 1.0000x reference)
.LBB0_1108:
	v_pk_add_f32 v[14:15], v[38:39], v[14:15] op_sel:[1,0] op_sel_hi:[0,1] neg_lo:[0,1] neg_hi:[0,1]
	v_pk_add_f32 v[16:17], v[40:41], v[16:17] op_sel:[1,0] op_sel_hi:[0,1] neg_lo:[0,1] neg_hi:[0,1]
	v_cvt_pk_bf16_f32 v14, v14, v15
	v_cvt_pk_bf16_f32 v15, v16, v17
	ds_write_b64 v185, v[14:15]
	s_waitcnt lgkmcnt(0)
	v_add_u32_e32 v14, 0, v22
	ds_read_b128 v[14:17], v14
	ds_read_b128 v[18:21], v186
	s_add_i32 s2, s2, -1
	s_waitcnt lgkmcnt(0)
	v_mfma_f32_16x16x32_bf16 v[14:17], v[14:17], v[18:21], 0
	v_add_u32_e32 v26, 0x1040, v26
	v_add_u32_e32 v25, 0x900, v25
	v_add_u32_e32 v24, 0x900, v24
	s_nop 4
	v_cvt_pk_bf16_f32 v14, v14, v15
	v_cvt_pk_bf16_f32 v15, v16, v17
	v_add_u32_e32 v16, 0, v23
	ds_write_b64 v16, v[14:15]
	s_waitcnt lgkmcnt(0)
	v_add_u32_e32 v23, 32, v23
	v_add_u32_e32 v22, 0x400, v22
	v_add_u32_e32 v1, 0x900, v1
	s_cmp_eq_u32 s2, 0
	s_cbranch_scc1 .LBB0_1113
.LBB0_1109:
	v_add_u32_e32 v27, 0, v1
	v_add_u32_e32 v14, 0x1b000, v27
	ds_read_b128 v[14:17], v14
	v_add_u32_e32 v32, s93, v117
	ds_read_b128 v[18:21], v32
	v_add_u32_e32 v27, 0x1b040, v27
	ds_read_b128 v[28:31], v27
	ds_read_b128 v[34:37], v32 offset:64
	s_andn2_b64 vcc, exec, s[56:57]
	s_cbranch_vccnz .Ls3_b
	v_add_u32_e32 v42, 0x1e400, v26
	v_add_u32_e32 v43, 0x1e504, v26
	v_add_u32_e32 v44, 0x1e608, v26
	v_add_u32_e32 v45, 0x1e70c, v26
	ds_read_b32 v39, v42
	ds_read_b32 v38, v43
	ds_read_b32 v41, v44
	ds_read_b32 v40, v45
	s_waitcnt lgkmcnt(6)
	v_mfma_f32_16x16x32_bf16 v[14:17], v[14:17], v[18:21], 0
	s_waitcnt lgkmcnt(4)
	v_mfma_f32_16x16x32_bf16 v[14:17], v[28:31], v[34:37], v[14:17]
	s_waitcnt lgkmcnt(0)
	s_nop 7
	s_branch .LBB0_1108
.Ls3_b:
	ds_read_u16 v42, v24
	ds_read_u16 v43, v25 offset:288
	ds_read_u16 v44, v25
	ds_read_u16 v45, v25 offset:144
	s_waitcnt lgkmcnt(6)
	v_mfma_f32_16x16x32_bf16 v[14:17], v[14:17], v[18:21], 0
	s_waitcnt lgkmcnt(4)
	v_mfma_f32_16x16x32_bf16 v[14:17], v[28:31], v[34:37], v[14:17]
	s_waitcnt lgkmcnt(0)
	v_lshlrev_b32_e32 v39, 16, v42
	v_lshlrev_b32_e32 v40, 16, v43
	v_lshlrev_b32_e32 v38, 16, v44
	v_lshlrev_b32_e32 v41, 16, v45
	s_nop 7
	s_branch .LBB0_1108
